# attention loop: one lgkmcnt wait per two K / V fragments instead of one per fragment
# baseline (speedup 1.0000x reference)
; #define LAS __attribute__((address_space(3)))
; __device__ __forceinline__ int my_tid() { int t = threadIdx.x; asm volatile("" : "+v"(t)); return t; }
; #define ATT_LOAD(tile) do { _Pragma("unroll") for (int i = 0; i < 2; ++i) { kr[i] = *(const u32x4*)(kg + (size_t)(64 * (tile) + 32 * i) * PP); vr[i] = *(const u32x4*)(vg + (size_t)(64 * (tile) + 32 * i) * PP); } } while (0)
; #define ATT_STORE(buf) do { LAS char* nb_ = lds + (buf) * ABUF; _Pragma("unroll") for (int i = 0; i < 2; ++i) { *(LAS u32x4*)(nb_ + soff + 32 * i * APIT) = kr[i]; *(LAS u32x4*)(nb_ + ATILE + soff + 32 * i * APIT) = vr[i]; } } while (0)
; __device__ __forceinline__ void attn_item(LAS char* lds, bf16_t* proj, int bl, int h, int qb, float lam, float oscale, const float* gdh, float smax) {
;     const int tid = my_tid(), lane = tid & 63, wid = __builtin_amdgcn_readfirstlane(tid >> 6), g = lane >> 4, fr = lane & 15;
;     const size_t rowbase = (size_t)bl * SEQ; const int q0 = qb * 128, qpos = q0 + 16 * wid + fr;
;     bf16_t* qp = proj + SEC(C_AQ) + (rowbase + qpos) * PP + h * 128;
;     bf16x8 qf[2][2];
; #pragma unroll
;     for (int c = 0; c < 2; ++c)
; #pragma unroll
;         for (int ks = 0; ks < 2; ++ks) qf[c][ks] = *(const bf16x8*)(qp + c * 64 + 32 * ks + 8 * g);
;     f32x4 O[2][8], Oe[2];
; #pragma unroll
;     for (int c = 0; c < 2; ++c) { Oe[c] = (f32x4){0.f, 0.f, 0.f, 0.f};
; #pragma unroll
;         for (int nb = 0; nb < 8; ++nb) O[c][nb] = (f32x4){0.f, 0.f, 0.f, 0.f}; }
;     const f32x4 negM = (f32x4){-smax, -smax, -smax, -smax};
;     const short one16 = (fr == 0) ? (short)0x3F80 : (short)0;
;     const bf16x8 onesf = (bf16x8){one16, one16, one16, one16, one16, one16, one16, one16};
;     const int NT = 2 * (qb + 1);
;     const int sr0 = tid >> 4, sc = tid & 15;
;     const bf16_t* kg = proj + SEC(C_AK) + (rowbase + sr0) * PP + h * 128 + sc * 8;
;     const bf16_t* vg = proj + SEC(C_AV) + (rowbase + sr0) * PP + h * 128 + sc * 8;
;     const int soff = sr0 * APIT + sc * 16;
;     u32x4 kr[2], vr[2];
;     ...
;     ATT_LOAD(0); ATT_STORE(0);
;     __syncthreads();
;     const int qmaxw = q0 + 16 * wid + 15;
;     int t = 0;
.LBB0_241:
	s_and_b32 s0, s40, 7
	s_lshl_b32 s44, s0, 8
	s_bfe_u32 s0, s41, 0x50003
	s_and_b32 s42, s41, 7
	s_and_b32 s1, s41, 0x100
	s_xor_b32 s4, s0, 31
	s_cmp_eq_u32 s1, 0
	v_mov_b32_e32 v14, v194
	s_cselect_b32 s45, s0, s4
	s_lshl_b32 s46, s45, 7
	v_readfirstlane_b32 s4, v14
	s_ashr_i32 s4, s4, 2
	s_and_b32 s43, s4, -16
	s_ashr_i32 s36, s41, 8
	v_and_b32_e32 v176, 15, v14
	s_add_i32 s43, s43, s46
	s_ashr_i32 s37, s36, 31
	v_or_b32_e32 v164, s43, v176
	s_lshl_b64 s[0:1], s[36:37], 12
	v_ashrrev_i32_e32 v165, 31, v164
	v_lshl_add_u64 v[162:163], s[0:1], 0, v[164:165]
	v_readlane_b32 s4, v252, 28
	v_lshlrev_b64 v[6:7], 11, v[162:163]
	v_readlane_b32 s5, v252, 29
	s_lshl_b32 s84, s42, 8
	v_lshlrev_b32_e32 v0, 4, v176
	v_lshl_add_u64 v[6:7], s[4:5], 0, v[6:7]
	v_lshl_add_u64 v[8:9], v[6:7], 0, s[84:85]
	v_ashrrev_i32_e32 v6, 4, v14
	v_ashrrev_i32_e32 v7, 31, v6
	v_lshl_add_u64 v[10:11], s[0:1], 0, v[6:7]
	v_readlane_b32 s0, v252, 30
	v_lshlrev_b64 v[10:11], 11, v[10:11]
	v_readlane_b32 s1, v252, 31
	v_and_b32_e32 v166, 48, v14
	v_mov_b32_e32 v167, v1
	v_lshl_add_u64 v[12:13], s[0:1], 0, v[10:11]
	v_readlane_b32 s0, v252, 32
	v_readlane_b32 s1, v252, 33
	v_lshl_add_u64 v[12:13], v[12:13], 0, s[84:85]
	v_lshl_add_u64 v[12:13], v[12:13], 0, v[0:1]
	v_lshl_add_u64 v[10:11], s[0:1], 0, v[10:11]
	v_lshl_add_u64 v[10:11], v[10:11], 0, s[84:85]
	s_mov_b32 s0, 0x10000
	v_lshl_add_u64 v[10:11], v[10:11], 0, v[0:1]
	global_load_dwordx4 v[118:121], v[12:13], off
	global_load_dwordx4 v[114:117], v[10:11], off
	v_add_co_u32_e32 v12, vcc, s0, v12
	v_lshl_add_u64 v[8:9], v[8:9], 0, v[166:167]
	s_nop 0
	v_addc_co_u32_e32 v13, vcc, 0, v13, vcc
	v_add_co_u32_e32 v10, vcc, s0, v10
	s_movk_i32 s0, 0x120
	s_nop 0
	v_addc_co_u32_e32 v11, vcc, 0, v11, vcc
	global_load_dwordx4 v[122:125], v[12:13], off
	global_load_dwordx4 v[126:129], v[10:11], off
	global_load_dwordx4 v[34:37], v[8:9], off
	global_load_dwordx4 v[38:41], v[8:9], off offset:64
	global_load_dwordx4 v[42:45], v[8:9], off offset:128
	global_load_dwordx4 v[50:53], v[8:9], off offset:192
	v_cmp_eq_u32_e32 vcc, 0, v176
	v_mov_b32_e32 v11, 0x3f80
	v_and_b32_e32 v8, 63, v14
	v_cndmask_b32_e32 v11, 0, v11, vcc
	v_mul_lo_u32 v12, v6, s0
	s_mov_b32 s0, 0x5040100
	v_bfe_u32 v9, v14, 2, 4
	v_lshlrev_b32_e32 v10, 3, v14
	v_or_b32_e32 v8, 48, v8
	v_perm_b32 v74, v11, v11, s0
	v_mul_u32_u24_e32 v167, 0x120, v176
	v_and_b32_e32 v165, 12, v9
	v_mul_u32_u24_e32 v177, 0x120, v9
	v_and_b32_e32 v178, 24, v10
	v_add3_u32 v179, v12, v0, 0
	v_mul_u32_u24_e32 v180, 0x120, v8
	v_mov_b32_e32 v75, v74
	v_mov_b32_e32 v76, v74
	v_mov_b32_e32 v77, v74
	s_cmp_lg_u32 s45, 0
	v_lshlrev_b64 v[170:171], 11, v[6:7]
	s_waitcnt vmcnt(7)
	ds_write_b128 v179, v[118:121]
	s_waitcnt vmcnt(6)
	ds_write_b128 v179, v[114:117] offset:18432
	s_waitcnt vmcnt(5)
	ds_write_b128 v179, v[122:125] offset:9216
	s_waitcnt vmcnt(4)
	ds_write_b128 v179, v[126:129] offset:27648
	s_waitcnt lgkmcnt(0)
	s_barrier
	s_cbranch_scc0 .LBB0_259
	s_lshl_b64 s[38:39], s[36:37], 23
	v_lshlrev_b64 v[168:169], 11, v[6:7]
	v_lshl_add_u64 v[6:7], s[38:39], 0, v[168:169]
	v_or_b32_e32 v6, s44, v6
	v_readlane_b32 s0, v254, 29
	v_lshl_add_u64 v[6:7], v[6:7], 0, v[0:1]
	v_readlane_b32 s1, v254, 30
	v_mov_b32_e32 v86, 0
	s_mov_b32 s47, 0
	v_lshl_add_u64 v[172:173], s[0:1], 0, v[6:7]
	s_mov_b32 s48, 1
	v_mov_b32_e32 v87, v86
	v_mov_b32_e32 v88, v86
	v_mov_b32_e32 v89, v86
	v_mov_b32_e32 v66, v86
	v_mov_b32_e32 v67, v86
	v_mov_b32_e32 v68, v86
	v_mov_b32_e32 v69, v86
	v_mov_b32_e32 v10, v86
	v_mov_b32_e32 v11, v86
	v_mov_b32_e32 v12, v86
	v_mov_b32_e32 v13, v86
	v_mov_b32_e32 v6, v86
	v_mov_b32_e32 v7, v86
	v_mov_b32_e32 v8, v86
	v_mov_b32_e32 v9, v86
	v_mov_b32_e32 v14, v86
	v_mov_b32_e32 v15, v86
	v_mov_b32_e32 v16, v86
	v_mov_b32_e32 v17, v86
	v_mov_b32_e32 v18, v86
	v_mov_b32_e32 v19, v86
	v_mov_b32_e32 v20, v86
	v_mov_b32_e32 v21, v86
	v_mov_b32_e32 v22, v86
	v_mov_b32_e32 v23, v86
	v_mov_b32_e32 v24, v86
	v_mov_b32_e32 v25, v86
	v_mov_b32_e32 v26, v86
	v_mov_b32_e32 v27, v86
	v_mov_b32_e32 v28, v86
	v_mov_b32_e32 v29, v86
	v_mov_b32_e32 v30, v86
	v_mov_b32_e32 v31, v86
	v_mov_b32_e32 v32, v86
	v_mov_b32_e32 v33, v86
	v_mov_b32_e32 v46, v86
	v_mov_b32_e32 v47, v86
	v_mov_b32_e32 v48, v86
	v_mov_b32_e32 v49, v86
	v_mov_b32_e32 v54, v86
	v_mov_b32_e32 v55, v86
	v_mov_b32_e32 v56, v86
	v_mov_b32_e32 v57, v86
	v_mov_b32_e32 v58, v86
	v_mov_b32_e32 v59, v86
	v_mov_b32_e32 v60, v86
	v_mov_b32_e32 v61, v86
	v_mov_b32_e32 v62, v86
	v_mov_b32_e32 v63, v86
	v_mov_b32_e32 v64, v86
	v_mov_b32_e32 v65, v86
	v_mov_b32_e32 v70, v86
	v_mov_b32_e32 v71, v86
	v_mov_b32_e32 v72, v86
	v_mov_b32_e32 v73, v86
	v_mov_b32_e32 v78, v86
	v_mov_b32_e32 v79, v86
	v_mov_b32_e32 v80, v86
	v_mov_b32_e32 v81, v86
	v_mov_b32_e32 v90, v86
	v_mov_b32_e32 v91, v86
	v_mov_b32_e32 v92, v86
	v_mov_b32_e32 v93, v86
	v_mov_b32_e32 v94, v86
	v_mov_b32_e32 v95, v86
	v_mov_b32_e32 v96, v86
	v_mov_b32_e32 v97, v86
	v_mov_b32_e32 v82, v86
	v_mov_b32_e32 v83, v86
	v_mov_b32_e32 v84, v86
	v_mov_b32_e32 v85, v86
	v_add_u32_e32 v230, v166, v167
	v_add_u32_e32 v231, v177, v178
	s_mov_b32 s4, 0xfdff0000
	s_mov_b32 s5, -1
	s_mov_b32 s6, 0xfe000000
	s_mov_b32 s7, -1
	s_mov_b32 s8, 0xfffd0000
	s_mov_b32 s9, -1
	s_mov_b32 s10, 0xfffe0000
	s_mov_b32 s11, -1
	s_mov_b32 s49, 0
	s_mov_b32 s50, 0x9000
	v_add_u32_e32 v181, s49, v230
	ds_read_b128 v[206:209], v181
	ds_read_b128 v[210:213], v181 offset:64
	ds_read_b128 v[214:217], v181 offset:4608
	ds_read_b128 v[218:221], v181 offset:4672
	ds_read_b128 v[222:225], v181 offset:9216
	v_lshl_add_u64 v[240:241], v[172:173], 0, s[4:5]
	global_load_dwordx4 v[146:149], v[240:241], off
	v_lshl_add_u64 v[240:241], v[172:173], 0, s[6:7]
	global_load_dwordx4 v[150:153], v[240:241], off
	v_lshl_add_u64 v[172:173], v[172:173], 0, s[76:77]
	s_waitcnt vmcnt(2)
; #define LAS __attribute__((address_space(3)))
; __device__ __forceinline__ f32x4 mfma16(bf16x8 a, bf16x8 b, f32x4 c) { return __builtin_amdgcn_mfma_f32_16x16x32_bf16(a, b, c, 0, 0, 0); }
; __device__ __forceinline__ void attn_step_fast(const LAS char* Kb, const LAS char* Vb, int lane, const bf16x8 (&qf)[2][2], const f32x4 negM, const bf16x8 onesf, f32x4 (&O)[2][8], f32x4 (&Oe)[2]) {
;     f32x4 s0[4], s1[4];
;     bf16x8 p0[2], p1[2];
;     {
;         bf16x8 kf[2][4][2];
; #pragma unroll
;         for (int c = 0; c < 2; ++c)
; #pragma unroll
;             for (int kb = 0; kb < 4; ++kb)
; #pragma unroll
;                 for (int ks = 0; ks < 2; ++ks) kf[c][kb][ks] = rowfrag(Kb, APIT, 16 * kb, c * 64 + 32 * ks, lane);
;         __builtin_amdgcn_sched_barrier(0);
; #pragma unroll
;         for (int kb = 0; kb < 4; ++kb) s0[kb] = mfma16(kf[0][kb][0], qf[0][0], negM);
; #pragma unroll
;         for (int kb = 0; kb < 4; ++kb) s0[kb] = mfma16(kf[0][kb][1], qf[0][1], s0[kb]);
;         __builtin_amdgcn_sched_barrier(0);
; #pragma unroll
;         for (int kb = 0; kb < 4; ++kb) s1[kb] = mfma16(kf[1][kb][0], qf[1][0], negM);
; #pragma unroll
;         for (int kb = 0; kb < 4; ++kb) s1[kb] = mfma16(kf[1][kb][1], qf[1][1], s1[kb]);
;     }
	s_waitcnt lgkmcnt(3)
	v_mfma_f32_16x16x32_bf16 v[98:101], v[206:209], v[34:37], v[2:5]
	ds_read_b128 v[206:209], v181 offset:9280
	v_mfma_f32_16x16x32_bf16 v[98:101], v[210:213], v[38:41], v[98:101]
	ds_read_b128 v[210:213], v181 offset:13824
	s_waitcnt lgkmcnt(3)
	v_mfma_f32_16x16x32_bf16 v[102:105], v[214:217], v[34:37], v[2:5]
	ds_read_b128 v[214:217], v181 offset:13888
	v_mfma_f32_16x16x32_bf16 v[102:105], v[218:221], v[38:41], v[102:105]
	ds_read_b128 v[218:221], v181 offset:128
	s_waitcnt lgkmcnt(3)
	v_mfma_f32_16x16x32_bf16 v[106:109], v[222:225], v[34:37], v[2:5]
	ds_read_b128 v[222:225], v181 offset:192
	v_mfma_f32_16x16x32_bf16 v[106:109], v[206:209], v[38:41], v[106:109]
	ds_read_b128 v[206:209], v181 offset:4736
	s_waitcnt lgkmcnt(3)
	v_mfma_f32_16x16x32_bf16 v[110:113], v[210:213], v[34:37], v[2:5]
	ds_read_b128 v[210:213], v181 offset:4800
	v_mfma_f32_16x16x32_bf16 v[110:113], v[214:217], v[38:41], v[110:113]
	ds_read_b128 v[214:217], v181 offset:9344
	s_waitcnt lgkmcnt(3)
	v_mfma_f32_16x16x32_bf16 v[114:117], v[218:221], v[42:45], v[2:5]
	ds_read_b128 v[218:221], v181 offset:9408
	v_mfma_f32_16x16x32_bf16 v[114:117], v[222:225], v[50:53], v[114:117]
	ds_read_b128 v[222:225], v181 offset:13952
	s_waitcnt lgkmcnt(3)
	v_mfma_f32_16x16x32_bf16 v[118:121], v[206:209], v[42:45], v[2:5]
	ds_read_b128 v[206:209], v181 offset:14016
	v_mfma_f32_16x16x32_bf16 v[118:121], v[210:213], v[50:53], v[118:121]
	s_waitcnt lgkmcnt(2)
	v_mfma_f32_16x16x32_bf16 v[122:125], v[214:217], v[42:45], v[2:5]
	v_mfma_f32_16x16x32_bf16 v[122:125], v[218:221], v[50:53], v[122:125]
	s_waitcnt lgkmcnt(0)
	v_mfma_f32_16x16x32_bf16 v[126:129], v[222:225], v[42:45], v[2:5]
	v_mfma_f32_16x16x32_bf16 v[126:129], v[206:209], v[50:53], v[126:129]
	v_add_u32_e32 v238, s50, v179
	s_nop 7
	v_exp_f32_e32 v98, v98
	v_exp_f32_e32 v99, v99
	v_exp_f32_e32 v100, v100
	v_exp_f32_e32 v101, v101
	v_exp_f32_e32 v114, v114
	v_exp_f32_e32 v115, v115
	v_exp_f32_e32 v116, v116
	v_exp_f32_e32 v117, v117
	v_exp_f32_e32 v102, v102
	v_exp_f32_e32 v103, v103
	v_exp_f32_e32 v104, v104
	v_exp_f32_e32 v105, v105
	v_exp_f32_e32 v118, v118
	v_exp_f32_e32 v119, v119
	v_exp_f32_e32 v120, v120
	v_exp_f32_e32 v121, v121
	v_exp_f32_e32 v106, v106
	v_exp_f32_e32 v107, v107
	v_exp_f32_e32 v108, v108
	v_exp_f32_e32 v109, v109
	v_exp_f32_e32 v122, v122
	v_exp_f32_e32 v123, v123
	v_exp_f32_e32 v124, v124
	v_exp_f32_e32 v125, v125
	v_exp_f32_e32 v110, v110
	v_exp_f32_e32 v111, v111
	v_exp_f32_e32 v112, v112
	v_exp_f32_e32 v113, v113
	v_exp_f32_e32 v126, v126
	v_exp_f32_e32 v127, v127
	v_exp_f32_e32 v128, v128
	v_exp_f32_e32 v129, v129
	v_cvt_pk_bf16_f32 v130, v98, v99
	v_cvt_pk_bf16_f32 v131, v100, v101
	v_cvt_pk_bf16_f32 v132, v102, v103
	v_cvt_pk_bf16_f32 v133, v104, v105
	v_cvt_pk_bf16_f32 v138, v114, v115
	v_cvt_pk_bf16_f32 v139, v116, v117
	v_cvt_pk_bf16_f32 v140, v118, v119
	v_cvt_pk_bf16_f32 v141, v120, v121
	s_waitcnt vmcnt(1)
	ds_write_b128 v238, v[146:149]
	s_waitcnt vmcnt(0)
	ds_write_b128 v238, v[150:153] offset:9216
	s_waitcnt lgkmcnt(0)
	s_barrier
	s_lshl_b32 s47, s45, 1
	s_add_i32 s47, s47, -1
	s_mov_b32 s49, 0x9000
	s_mov_b32 s50, 0
.Lmy_attn_loop:
	v_add_u32_e32 v181, s49, v230
	v_add_u32_e32 v205, s50, v231
	ds_read_b128 v[206:209], v181
	ds_read_b128 v[210:213], v181 offset:64
	ds_read_b128 v[214:217], v181 offset:4608
	ds_read_b128 v[218:221], v181 offset:4672
	ds_read_b128 v[222:225], v181 offset:9216
	v_lshl_add_u64 v[240:241], v[172:173], 0, s[4:5]
	global_load_dwordx4 v[146:149], v[240:241], off
	v_lshl_add_u64 v[240:241], v[172:173], 0, s[6:7]
	global_load_dwordx4 v[150:153], v[240:241], off
	v_lshl_add_u64 v[240:241], v[172:173], 0, s[8:9]
	global_load_dwordx4 v[154:157], v[240:241], off
	v_lshl_add_u64 v[240:241], v[172:173], 0, s[10:11]
	global_load_dwordx4 v[158:161], v[240:241], off
	v_lshl_add_u64 v[172:173], v[172:173], 0, s[76:77]
	v_cvt_pk_bf16_f32 v134, v106, v107
	v_cvt_pk_bf16_f32 v135, v108, v109
	v_cvt_pk_bf16_f32 v136, v110, v111
	v_cvt_pk_bf16_f32 v137, v112, v113
	v_cvt_pk_bf16_f32 v142, v122, v123
	v_cvt_pk_bf16_f32 v143, v124, v125
	v_cvt_pk_bf16_f32 v144, v126, v127
	v_cvt_pk_bf16_f32 v145, v128, v129
	s_waitcnt lgkmcnt(3)
	v_mfma_f32_16x16x32_bf16 v[98:101], v[206:209], v[34:37], v[2:5]
	ds_read_b128 v[206:209], v181 offset:9280
	v_mfma_f32_16x16x32_bf16 v[98:101], v[210:213], v[38:41], v[98:101]
	ds_read_b128 v[210:213], v181 offset:13824
	s_waitcnt lgkmcnt(3)
	v_mfma_f32_16x16x32_bf16 v[102:105], v[214:217], v[34:37], v[2:5]
	ds_read_b128 v[214:217], v181 offset:13888
	v_mfma_f32_16x16x32_bf16 v[102:105], v[218:221], v[38:41], v[102:105]
	ds_read_b128 v[218:221], v181 offset:128
	s_waitcnt lgkmcnt(3)
	v_mfma_f32_16x16x32_bf16 v[106:109], v[222:225], v[34:37], v[2:5]
	ds_read_b128 v[222:225], v181 offset:192
	v_mfma_f32_16x16x32_bf16 v[106:109], v[206:209], v[38:41], v[106:109]
	ds_read_b128 v[206:209], v181 offset:4736
	s_waitcnt lgkmcnt(3)
	v_mfma_f32_16x16x32_bf16 v[110:113], v[210:213], v[34:37], v[2:5]
	ds_read_b128 v[210:213], v181 offset:4800
	v_mfma_f32_16x16x32_bf16 v[110:113], v[214:217], v[38:41], v[110:113]
	ds_read_b128 v[214:217], v181 offset:9344
	s_waitcnt lgkmcnt(3)
	v_mfma_f32_16x16x32_bf16 v[114:117], v[218:221], v[42:45], v[2:5]
	ds_read_b128 v[218:221], v181 offset:9408
	v_mfma_f32_16x16x32_bf16 v[114:117], v[222:225], v[50:53], v[114:117]
	ds_read_b128 v[222:225], v181 offset:13952
	s_waitcnt lgkmcnt(3)
	v_mfma_f32_16x16x32_bf16 v[118:121], v[206:209], v[42:45], v[2:5]
	ds_read_b128 v[206:209], v181 offset:14016
	ds_read_b64_tr_b16 v[182:183], v205 offset:18432
	ds_read_b64_tr_b16 v[184:185], v205 offset:23040
	v_mfma_f32_16x16x32_bf16 v[118:121], v[210:213], v[50:53], v[118:121]
	ds_read_b64_tr_b16 v[186:187], v205 offset:18464
	ds_read_b64_tr_b16 v[188:189], v205 offset:23072
	s_waitcnt lgkmcnt(6)
; __device__ __forceinline__ f32x4 mfma16(bf16x8 a, bf16x8 b, f32x4 c) { return __builtin_amdgcn_mfma_f32_16x16x32_bf16(a, b, c, 0, 0, 0); }
; __device__ __forceinline__ void attn_step_fast(const LAS char* Kb, const LAS char* Vb, int lane, const bf16x8 (&qf)[2][2], const f32x4 negM, const bf16x8 onesf, f32x4 (&O)[2][8], f32x4 (&Oe)[2]) {
;     ...
;     bf16x8 va[8], vb[8];
; #pragma unroll
;     for (int nb = 0; nb < 8; ++nb) va[nb] = trfrag(Vb, APIT, 0, 16 * nb, lane);
; #pragma unroll
;     for (int nb = 0; nb < 8; ++nb) vb[nb] = trfrag(Vb, APIT, 32, 16 * nb, lane);
;     __builtin_amdgcn_sched_barrier(0);
;     Oe[0] = mfma16(onesf, p0[0], Oe[0]);
; #pragma unroll
;     for (int nb = 0; nb < 8; ++nb) O[0][nb] = mfma16(va[nb], p0[0], O[0][nb]);
;     Oe[0] = mfma16(onesf, p0[1], Oe[0]);
; #pragma unroll
;     for (int nb = 0; nb < 8; ++nb) O[0][nb] = mfma16(vb[nb], p0[1], O[0][nb]);
;     ATT_EXPPACK(s1, p1);
; #pragma unroll
;     for (int i = 0; i < 18; ++i) { __builtin_amdgcn_sched_group_barrier(0x008, 1, 0); __builtin_amdgcn_sched_group_barrier(0x002, 2, 0); }
;     __builtin_amdgcn_sched_barrier(0);
;     Oe[1] = mfma16(onesf, p1[0], Oe[1]);
; #pragma unroll
;     for (int nb = 0; nb < 8; ++nb) O[1][nb] = mfma16(va[nb], p1[0], O[1][nb]);
;     Oe[1] = mfma16(onesf, p1[1], Oe[1]);
; #pragma unroll
;     for (int nb = 0; nb < 8; ++nb) O[1][nb] = mfma16(vb[nb], p1[1], O[1][nb]);
	v_mfma_f32_16x16x32_bf16 v[122:125], v[214:217], v[42:45], v[2:5]
	ds_read_b64_tr_b16 v[190:191], v205 offset:18496
	ds_read_b64_tr_b16 v[192:193], v205 offset:23104
	v_mfma_f32_16x16x32_bf16 v[122:125], v[218:221], v[50:53], v[122:125]
	ds_read_b64_tr_b16 v[226:227], v205 offset:18528
	ds_read_b64_tr_b16 v[228:229], v205 offset:23136
	s_waitcnt lgkmcnt(8)
	v_mfma_f32_16x16x32_bf16 v[126:129], v[222:225], v[42:45], v[2:5]
	ds_read_b64_tr_b16 v[244:245], v205 offset:18560
	ds_read_b64_tr_b16 v[246:247], v205 offset:23168
	v_mfma_f32_16x16x32_bf16 v[126:129], v[206:209], v[50:53], v[126:129]
	ds_read_b64_tr_b16 v[248:249], v205 offset:18592
	ds_read_b64_tr_b16 v[250:251], v205 offset:23200
	v_add_u32_e32 v238, s50, v179
	v_add_u32_e32 v239, s49, v179
	v_mfma_f32_16x16x32_bf16 v[94:97], v[74:77], v[130:133], v[94:97]
	v_exp_f32_e32 v98, v98
	v_mfma_f32_16x16x32_bf16 v[90:93], v[74:77], v[138:141], v[90:93]
	v_exp_f32_e32 v99, v99
	s_waitcnt lgkmcnt(8)
	v_mfma_f32_16x16x32_bf16 v[82:85], v[182:185], v[130:133], v[82:85]
	v_exp_f32_e32 v100, v100
	v_mfma_f32_16x16x32_bf16 v[78:81], v[182:185], v[138:141], v[78:81]
	ds_read_b64_tr_b16 v[182:183], v205 offset:18624
	ds_read_b64_tr_b16 v[184:185], v205 offset:23232
	v_exp_f32_e32 v101, v101
	v_mfma_f32_16x16x32_bf16 v[70:73], v[186:189], v[130:133], v[70:73]
	v_exp_f32_e32 v114, v114
	v_mfma_f32_16x16x32_bf16 v[62:65], v[186:189], v[138:141], v[62:65]
	ds_read_b64_tr_b16 v[186:187], v205 offset:18656
	ds_read_b64_tr_b16 v[188:189], v205 offset:23264
	v_exp_f32_e32 v115, v115
	s_waitcnt lgkmcnt(8)
	v_mfma_f32_16x16x32_bf16 v[58:61], v[190:193], v[130:133], v[58:61]
	v_exp_f32_e32 v116, v116
	v_mfma_f32_16x16x32_bf16 v[54:57], v[190:193], v[138:141], v[54:57]
	ds_read_b64_tr_b16 v[190:191], v205 offset:27648
	ds_read_b64_tr_b16 v[192:193], v205 offset:32256
	v_exp_f32_e32 v117, v117
	v_mfma_f32_16x16x32_bf16 v[46:49], v[226:229], v[130:133], v[46:49]
	v_exp_f32_e32 v102, v102
	v_mfma_f32_16x16x32_bf16 v[30:33], v[226:229], v[138:141], v[30:33]
	ds_read_b64_tr_b16 v[226:227], v205 offset:27680
	ds_read_b64_tr_b16 v[228:229], v205 offset:32288
	v_exp_f32_e32 v103, v103
	s_waitcnt lgkmcnt(8)
	v_mfma_f32_16x16x32_bf16 v[26:29], v[244:247], v[130:133], v[26:29]
	v_exp_f32_e32 v104, v104
	v_mfma_f32_16x16x32_bf16 v[22:25], v[244:247], v[138:141], v[22:25]
	ds_read_b64_tr_b16 v[244:245], v205 offset:27712
	ds_read_b64_tr_b16 v[246:247], v205 offset:32320
	v_exp_f32_e32 v105, v105
	v_mfma_f32_16x16x32_bf16 v[18:21], v[248:251], v[130:133], v[18:21]
	v_exp_f32_e32 v118, v118
	v_mfma_f32_16x16x32_bf16 v[14:17], v[248:251], v[138:141], v[14:17]
	ds_read_b64_tr_b16 v[248:249], v205 offset:27744
	ds_read_b64_tr_b16 v[250:251], v205 offset:32352
	v_exp_f32_e32 v119, v119
	s_waitcnt lgkmcnt(8)
	v_mfma_f32_16x16x32_bf16 v[6:9], v[182:185], v[130:133], v[6:9]
	v_exp_f32_e32 v120, v120
	v_mfma_f32_16x16x32_bf16 v[10:13], v[182:185], v[138:141], v[10:13]
	ds_read_b64_tr_b16 v[182:183], v205 offset:27776
	ds_read_b64_tr_b16 v[184:185], v205 offset:32384
	v_exp_f32_e32 v121, v121
	v_mfma_f32_16x16x32_bf16 v[66:69], v[186:189], v[130:133], v[66:69]
	v_exp_f32_e32 v106, v106
	v_mfma_f32_16x16x32_bf16 v[86:89], v[186:189], v[138:141], v[86:89]
	ds_read_b64_tr_b16 v[186:187], v205 offset:27808
	ds_read_b64_tr_b16 v[188:189], v205 offset:32416
	v_exp_f32_e32 v107, v107
	v_mfma_f32_16x16x32_bf16 v[94:97], v[74:77], v[134:137], v[94:97]
	v_exp_f32_e32 v108, v108
	v_mfma_f32_16x16x32_bf16 v[90:93], v[74:77], v[142:145], v[90:93]
	v_exp_f32_e32 v109, v109
	s_waitcnt lgkmcnt(8)
	v_mfma_f32_16x16x32_bf16 v[82:85], v[190:193], v[134:137], v[82:85]
	v_exp_f32_e32 v122, v122
	v_mfma_f32_16x16x32_bf16 v[78:81], v[190:193], v[142:145], v[78:81]
	ds_read_b64_tr_b16 v[190:191], v205 offset:27840
	ds_read_b64_tr_b16 v[192:193], v205 offset:32448
	v_exp_f32_e32 v123, v123
	v_mfma_f32_16x16x32_bf16 v[70:73], v[226:229], v[134:137], v[70:73]
	v_exp_f32_e32 v124, v124
	v_mfma_f32_16x16x32_bf16 v[62:65], v[226:229], v[142:145], v[62:65]
	ds_read_b64_tr_b16 v[226:227], v205 offset:27872
	ds_read_b64_tr_b16 v[228:229], v205 offset:32480
	v_exp_f32_e32 v125, v125
	s_waitcnt lgkmcnt(8)
	v_mfma_f32_16x16x32_bf16 v[58:61], v[244:247], v[134:137], v[58:61]
	v_exp_f32_e32 v110, v110
	v_mfma_f32_16x16x32_bf16 v[54:57], v[244:247], v[142:145], v[54:57]
	v_exp_f32_e32 v111, v111
	v_mfma_f32_16x16x32_bf16 v[46:49], v[248:251], v[134:137], v[46:49]
	v_exp_f32_e32 v112, v112
	v_mfma_f32_16x16x32_bf16 v[30:33], v[248:251], v[142:145], v[30:33]
	v_exp_f32_e32 v113, v113
	s_waitcnt lgkmcnt(4)
	v_mfma_f32_16x16x32_bf16 v[26:29], v[182:185], v[134:137], v[26:29]
	v_exp_f32_e32 v126, v126
	s_waitcnt vmcnt(3)
	ds_write_b128 v238, v[146:149]
	v_mfma_f32_16x16x32_bf16 v[22:25], v[182:185], v[142:145], v[22:25]
	v_exp_f32_e32 v127, v127
	v_mfma_f32_16x16x32_bf16 v[18:21], v[186:189], v[134:137], v[18:21]
	v_exp_f32_e32 v128, v128
	s_waitcnt vmcnt(2)
	ds_write_b128 v238, v[150:153] offset:9216
	v_mfma_f32_16x16x32_bf16 v[14:17], v[186:189], v[142:145], v[14:17]
	v_exp_f32_e32 v129, v129
	s_waitcnt lgkmcnt(2)
	v_mfma_f32_16x16x32_bf16 v[6:9], v[190:193], v[134:137], v[6:9]
	v_cvt_pk_bf16_f32 v130, v98, v99
	v_cvt_pk_bf16_f32 v131, v100, v101
	s_waitcnt vmcnt(1)
	ds_write_b128 v239, v[154:157] offset:18432
	v_mfma_f32_16x16x32_bf16 v[10:13], v[190:193], v[142:145], v[10:13]
	v_cvt_pk_bf16_f32 v132, v102, v103
	v_cvt_pk_bf16_f32 v133, v104, v105
	v_mfma_f32_16x16x32_bf16 v[66:69], v[226:229], v[134:137], v[66:69]
	v_cvt_pk_bf16_f32 v138, v114, v115
	v_cvt_pk_bf16_f32 v139, v116, v117
	s_waitcnt vmcnt(0)
	ds_write_b128 v239, v[158:161] offset:27648
	v_mfma_f32_16x16x32_bf16 v[86:89], v[226:229], v[142:145], v[86:89]
	v_cvt_pk_bf16_f32 v140, v118, v119
	v_cvt_pk_bf16_f32 v141, v120, v121
	s_waitcnt lgkmcnt(0)
	s_barrier
; #define LAS __attribute__((address_space(3)))
; __device__ __forceinline__ f32x4 mfma16(bf16x8 a, bf16x8 b, f32x4 c) { return __builtin_amdgcn_mfma_f32_16x16x32_bf16(a, b, c, 0, 0, 0); }
; #define BAR_LDS() do { asm volatile("s_waitcnt lgkmcnt(0)" ::: "memory"); __builtin_amdgcn_s_barrier(); asm volatile("" ::: "memory"); } while (0)
; #define ATT_LOAD(tile) do { _Pragma("unroll") for (int i = 0; i < 2; ++i) { kr[i] = *(const u32x4*)(kg + (size_t)(64 * (tile) + 32 * i) * PP); vr[i] = *(const u32x4*)(vg + (size_t)(64 * (tile) + 32 * i) * PP); } } while (0)
; #define ATT_STORE(buf) do { LAS char* nb_ = lds + (buf) * ABUF; _Pragma("unroll") for (int i = 0; i < 2; ++i) { *(LAS u32x4*)(nb_ + soff + 32 * i * APIT) = kr[i]; *(LAS u32x4*)(nb_ + ATILE + soff + 32 * i * APIT) = vr[i]; } } while (0)
; __device__ __forceinline__ void attn_pv(const LAS char* Vb, int lane, const bf16x8 (&pf)[2][2], const bf16x8 onesf, f32x4 (&O)[2][8], f32x4 (&Oe)[2]) {
;     bf16x8 va[8], vb[8];
; #pragma unroll
;     for (int nb = 0; nb < 8; ++nb) va[nb] = trfrag(Vb, APIT, 0, 16 * nb, lane);
; #pragma unroll
;     for (int nb = 0; nb < 8; ++nb) vb[nb] = trfrag(Vb, APIT, 32, 16 * nb, lane);
;     __builtin_amdgcn_sched_barrier(0);
;     Oe[0] = mfma16(onesf, pf[0][0], Oe[0]); Oe[1] = mfma16(onesf, pf[1][0], Oe[1]);
; #pragma unroll
;     for (int nb = 0; nb < 8; ++nb) { O[0][nb] = mfma16(va[nb], pf[0][0], O[0][nb]); O[1][nb] = mfma16(va[nb], pf[1][0], O[1][nb]); }
;     Oe[0] = mfma16(onesf, pf[0][1], Oe[0]); Oe[1] = mfma16(onesf, pf[1][1], Oe[1]);
; #pragma unroll
;     for (int nb = 0; nb < 8; ++nb) { O[0][nb] = mfma16(vb[nb], pf[0][1], O[0][nb]); O[1][nb] = mfma16(vb[nb], pf[1][1], O[1][nb]); }
; }
; __device__ __forceinline__ void attn_item(LAS char* lds, bf16_t* proj, int bl, int h, int qb, float lam, float oscale, const float* gdh, float smax) {
;     ...
;     for (; t < NT - 2; ++t) {
;         ATT_LOAD(t + 1);
;         const LAS char* Kb = lds + (t & 1) * ABUF;
;     ...
;         attn_step_fast(Kb, Kb + ATILE, lane, qf, negM, onesf, O, Oe);
;     ...
;         { bf16x8 pq[2][2]; attn_qkexp(Kb, 64 * t, q0, wid, lane, g, qpos, qf, negM, pq); attn_pv(Kb + ATILE, lane, pq, onesf, O, Oe); }
;     ...
;         ATT_STORE((t + 1) & 1);
;         BAR_LDS();
	s_xor_b32 s49, s49, 0x9000
	s_xor_b32 s50, s50, 0x9000
	s_add_i32 s47, s47, -1
	s_cmp_lg_u32 s47, 0
	s_cbranch_scc1 .Lmy_attn_loop
	v_add_u32_e32 v181, s49, v230
	v_add_u32_e32 v205, s50, v231
	v_lshl_add_u64 v[240:241], v[172:173], 0, s[8:9]
	global_load_dwordx4 v[154:157], v[240:241], off
	v_lshl_add_u64 v[240:241], v[172:173], 0, s[10:11]
	global_load_dwordx4 v[158:161], v[240:241], off
	v_cvt_pk_bf16_f32 v134, v106, v107
	v_cvt_pk_bf16_f32 v135, v108, v109
	v_cvt_pk_bf16_f32 v136, v110, v111
	v_cvt_pk_bf16_f32 v137, v112, v113
	v_cvt_pk_bf16_f32 v142, v122, v123
	v_cvt_pk_bf16_f32 v143, v124, v125
	v_cvt_pk_bf16_f32 v144, v126, v127
	v_cvt_pk_bf16_f32 v145, v128, v129
	ds_read_b64_tr_b16 v[182:183], v205 offset:18432
	ds_read_b64_tr_b16 v[184:185], v205 offset:23040
	ds_read_b64_tr_b16 v[186:187], v205 offset:18464
	ds_read_b64_tr_b16 v[188:189], v205 offset:23072
	ds_read_b64_tr_b16 v[190:191], v205 offset:18496
	ds_read_b64_tr_b16 v[192:193], v205 offset:23104
	ds_read_b64_tr_b16 v[226:227], v205 offset:18528
	ds_read_b64_tr_b16 v[228:229], v205 offset:23136
	ds_read_b64_tr_b16 v[244:245], v205 offset:18560
	ds_read_b64_tr_b16 v[246:247], v205 offset:23168
	ds_read_b64_tr_b16 v[248:249], v205 offset:18592
	ds_read_b64_tr_b16 v[250:251], v205 offset:23200
	v_add_u32_e32 v238, s50, v179
	v_add_u32_e32 v239, s49, v179
	v_mfma_f32_16x16x32_bf16 v[94:97], v[74:77], v[130:133], v[94:97]
	v_mfma_f32_16x16x32_bf16 v[90:93], v[74:77], v[138:141], v[90:93]
	s_waitcnt lgkmcnt(8)
	v_mfma_f32_16x16x32_bf16 v[82:85], v[182:185], v[130:133], v[82:85]
	v_mfma_f32_16x16x32_bf16 v[78:81], v[182:185], v[138:141], v[78:81]
	ds_read_b64_tr_b16 v[182:183], v205 offset:18624
	ds_read_b64_tr_b16 v[184:185], v205 offset:23232
	v_mfma_f32_16x16x32_bf16 v[70:73], v[186:189], v[130:133], v[70:73]
	v_mfma_f32_16x16x32_bf16 v[62:65], v[186:189], v[138:141], v[62:65]
	ds_read_b64_tr_b16 v[186:187], v205 offset:18656
	ds_read_b64_tr_b16 v[188:189], v205 offset:23264
	s_waitcnt lgkmcnt(8)
	v_mfma_f32_16x16x32_bf16 v[58:61], v[190:193], v[130:133], v[58:61]
	v_mfma_f32_16x16x32_bf16 v[54:57], v[190:193], v[138:141], v[54:57]
	ds_read_b64_tr_b16 v[190:191], v205 offset:27648
	ds_read_b64_tr_b16 v[192:193], v205 offset:32256
	v_mfma_f32_16x16x32_bf16 v[46:49], v[226:229], v[130:133], v[46:49]
	v_mfma_f32_16x16x32_bf16 v[30:33], v[226:229], v[138:141], v[30:33]
	ds_read_b64_tr_b16 v[226:227], v205 offset:27680
	ds_read_b64_tr_b16 v[228:229], v205 offset:32288
	s_waitcnt lgkmcnt(8)
	v_mfma_f32_16x16x32_bf16 v[26:29], v[244:247], v[130:133], v[26:29]
	v_mfma_f32_16x16x32_bf16 v[22:25], v[244:247], v[138:141], v[22:25]
	ds_read_b64_tr_b16 v[244:245], v205 offset:27712
	ds_read_b64_tr_b16 v[246:247], v205 offset:32320
	v_mfma_f32_16x16x32_bf16 v[18:21], v[248:251], v[130:133], v[18:21]
	v_mfma_f32_16x16x32_bf16 v[14:17], v[248:251], v[138:141], v[14:17]
	ds_read_b64_tr_b16 v[248:249], v205 offset:27744
	ds_read_b64_tr_b16 v[250:251], v205 offset:32352
	s_waitcnt lgkmcnt(8)
	v_mfma_f32_16x16x32_bf16 v[6:9], v[182:185], v[130:133], v[6:9]
	v_mfma_f32_16x16x32_bf16 v[10:13], v[182:185], v[138:141], v[10:13]
	ds_read_b64_tr_b16 v[182:183], v205 offset:27776
	ds_read_b64_tr_b16 v[184:185], v205 offset:32384
	v_mfma_f32_16x16x32_bf16 v[66:69], v[186:189], v[130:133], v[66:69]
	v_mfma_f32_16x16x32_bf16 v[86:89], v[186:189], v[138:141], v[86:89]
	ds_read_b64_tr_b16 v[186:187], v205 offset:27808
	ds_read_b64_tr_b16 v[188:189], v205 offset:32416
	v_mfma_f32_16x16x32_bf16 v[94:97], v[74:77], v[134:137], v[94:97]
	v_mfma_f32_16x16x32_bf16 v[90:93], v[74:77], v[142:145], v[90:93]
	s_waitcnt lgkmcnt(8)
	v_mfma_f32_16x16x32_bf16 v[82:85], v[190:193], v[134:137], v[82:85]
	v_mfma_f32_16x16x32_bf16 v[78:81], v[190:193], v[142:145], v[78:81]
	ds_read_b64_tr_b16 v[190:191], v205 offset:27840
	ds_read_b64_tr_b16 v[192:193], v205 offset:32448
	v_mfma_f32_16x16x32_bf16 v[70:73], v[226:229], v[134:137], v[70:73]
	v_mfma_f32_16x16x32_bf16 v[62:65], v[226:229], v[142:145], v[62:65]
	ds_read_b64_tr_b16 v[226:227], v205 offset:27872
	ds_read_b64_tr_b16 v[228:229], v205 offset:32480
	s_waitcnt lgkmcnt(8)
	v_mfma_f32_16x16x32_bf16 v[58:61], v[244:247], v[134:137], v[58:61]
	v_mfma_f32_16x16x32_bf16 v[54:57], v[244:247], v[142:145], v[54:57]
	v_mfma_f32_16x16x32_bf16 v[46:49], v[248:251], v[134:137], v[46:49]
	v_mfma_f32_16x16x32_bf16 v[30:33], v[248:251], v[142:145], v[30:33]
	s_waitcnt lgkmcnt(4)
	v_mfma_f32_16x16x32_bf16 v[26:29], v[182:185], v[134:137], v[26:29]
	s_waitcnt vmcnt(1)
	ds_write_b128 v239, v[154:157] offset:18432
	v_mfma_f32_16x16x32_bf16 v[22:25], v[182:185], v[142:145], v[22:25]
	v_mfma_f32_16x16x32_bf16 v[18:21], v[186:189], v[134:137], v[18:21]
	s_waitcnt vmcnt(0)
	ds_write_b128 v239, v[158:161] offset:27648
	v_mfma_f32_16x16x32_bf16 v[14:17], v[186:189], v[142:145], v[14:17]
	s_waitcnt lgkmcnt(2)
	v_mfma_f32_16x16x32_bf16 v[6:9], v[190:193], v[134:137], v[6:9]
	v_mfma_f32_16x16x32_bf16 v[10:13], v[190:193], v[142:145], v[10:13]
	v_mfma_f32_16x16x32_bf16 v[66:69], v[226:229], v[134:137], v[66:69]
	v_mfma_f32_16x16x32_bf16 v[86:89], v[226:229], v[142:145], v[86:89]
	s_waitcnt lgkmcnt(0)
	s_barrier
